# s12 + attention: K half of the staged tile written to LDS before the first barrier (K buffer already free), V half between the barriers
# speedup vs baseline: 1.0020x; 1.0020x over previous
; #define SBAR() __builtin_amdgcn_sched_barrier(0)
; #define SLOAD(i, k0) do { sr_[i].vs0 = St::ld8(&Vh[(long)((k0) + sr) * LDK + sc]); sr_[i].vs1 = St::ld8(&Vh[(long)((k0) + 32 + sr) * LDK + sc]); \
;     sr_[i].ks0 = St::ld8(&Kh[(long)((k0) + sr) * LDK + sc]); sr_[i].ks1 = St::ld8(&Kh[(long)((k0) + 32 + sr) * LDK + sc]); } while (0)
; __device__ __forceinline__ void finishSM(f32x16& p0, f32x16& p1, float alpha, float& l_reg, bf16x8& pa0, bf16x8& pa1, bf16x8& pa2, bf16x8& pa3) {
;   for (int r = 0; r < 16; ++r) p1[r] = __builtin_amdgcn_exp2f(p1[r]);
;   float ps = 0; for (int r = 0; r < 16; ++r) ps += p0[r]; for (int r = 0; r < 16; ++r) ps += p1[r];
;   { auto rr = __builtin_amdgcn_permlane32_swap(__float_as_uint(ps), __float_as_uint(ps), false, false);
;     ps = __uint_as_float(rr[0]) + __uint_as_float(rr[1]); }
;   l_reg = l_reg * alpha + ps;
;     ...
;   PK4(p0, 0, pa0); PK4(p0, 8, pa1); PK4(p1, 0, pa2); PK4(p1, 8, pa3);
;     ...
; }
; __device__ __forceinline__ void qkt(f32x16& p0, f32x16& p1, const bf16* Ks, const bf16x8* qr, int r32, int hi) {
;   p0 = f32x16{}; p1 = f32x16{};
;   for (int d0 = 0; d0 < 8; ++d0) { int cb = (d0 * 16 + hi * 8) * 2;
;     bf16x8 b0 = *reinterpret_cast<const bf16x8*>((const char*)Ks + KSWZ(r32, cb));
;     bf16x8 b1 = *reinterpret_cast<const bf16x8*>((const char*)Ks + KSWZ(32 + r32, cb));
;     p0 = __builtin_amdgcn_mfma_f32_32x32x16_bf16(b0, qr[d0], p0, 0, 0, 0);
;     p1 = __builtin_amdgcn_mfma_f32_32x32x16_bf16(b1, qr[d0], p1, 0, 0, 0); }
; }
; __device__ __forceinline__ void attn_dense_body(const bf16* __restrict__ Qb, const bf16* __restrict__ Kh, const bf16* __restrict__ Vh,
;                                                 const unsigned short* __restrict__ Gb, unsigned short* __restrict__ Yb, int seq, char* lds, const int tid) {
;     ...
;     SBAR(); qkt(pB0, pB1, (bf16*)((char*)K_lds + SHM_K), qr, r32, hi);
;     finishSM(pA0, pA1, alA, l_reg, pa0, pa1, pa2, pa3); SBAR();
;     SLOAD(SO, (j + SDEPTH) * KVBLK); SBAR();
;     pv_d0(o, vb0, pa0, pa1, pa2, pa3); partialSM(pB0, pB1, m_reg, mnB, alB);
.LBB0_602:
	ds_read_b128 v[64:67], v192 offset:49152
	ds_read_b128 v[68:71], v192 offset:57344
	ds_read_b128 v[146:149], v201 offset:49152
	ds_read_b128 v[150:153], v201 offset:57344
	v_exp_f32_e32 v160, v162
	v_add_f32_e32 v162, 0, v223
	s_waitcnt lgkmcnt(3)
	v_mfma_f32_32x32x16_bf16 v[80:95], v[64:67], v[126:129], 0
	v_add_f32_e32 v162, v224, v162
	v_add_f32_e32 v162, v225, v162
	v_add_f32_e32 v162, v227, v162
	v_add_f32_e32 v162, v229, v162
	v_add_f32_e32 v162, v230, v162
	v_add_f32_e32 v162, v226, v162
	v_add_f32_e32 v162, v228, v162
	s_waitcnt lgkmcnt(2)
	v_mfma_f32_32x32x16_bf16 v[64:79], v[68:71], v[126:129], 0
	v_add_f32_e32 v162, v215, v162
	v_add_f32_e32 v162, v217, v162
	v_add_f32_e32 v162, v219, v162
	v_add_f32_e32 v162, v221, v162
	v_add_f32_e32 v162, v216, v162
	v_add_f32_e32 v162, v218, v162
	v_add_f32_e32 v162, v220, v162
	s_waitcnt lgkmcnt(1)
	v_mfma_f32_32x32x16_bf16 v[80:95], v[146:149], v[122:125], v[80:95]
	v_add_f32_e32 v162, v222, v162
	v_exp_f32_e32 v154, v164
	v_exp_f32_e32 v155, v165
	v_exp_f32_e32 v156, v172
	v_exp_f32_e32 v157, v173
	v_exp_f32_e32 v158, v168
	v_exp_f32_e32 v159, v169
	s_waitcnt lgkmcnt(0)
	v_mfma_f32_32x32x16_bf16 v[64:79], v[150:153], v[122:125], v[64:79]
	ds_read_b128 v[146:149], v200 offset:49152
	ds_read_b128 v[150:153], v200 offset:57344
	v_exp_f32_e32 v161, v163
	v_cvt_pk_bf16_f32 v164, v229, v230
	v_cvt_pk_bf16_f32 v163, v225, v227
	v_cvt_pk_bf16_f32 v165, v226, v228
	v_cvt_pk_bf16_f32 v168, v216, v218
	v_cvt_pk_bf16_f32 v169, v220, v222
	s_waitcnt lgkmcnt(1)
	v_mfma_f32_32x32x16_bf16 v[80:95], v[146:149], v[134:137], v[80:95]
	v_permlane32_swap_b32_e32 v163, v165
	s_waitcnt lgkmcnt(0)
	v_mfma_f32_32x32x16_bf16 v[64:79], v[150:153], v[134:137], v[64:79]
	ds_read_b128 v[146:149], v195 offset:49152
	ds_read_b128 v[150:153], v195 offset:57344
	s_waitcnt lgkmcnt(1)
	v_mfma_f32_32x32x16_bf16 v[80:95], v[146:149], v[130:133], v[80:95]
	s_waitcnt lgkmcnt(0)
	v_mfma_f32_32x32x16_bf16 v[64:79], v[150:153], v[130:133], v[64:79]
	ds_read_b128 v[146:149], v194 offset:49152
	ds_read_b128 v[150:153], v194 offset:57344
	s_waitcnt lgkmcnt(1)
	v_mfma_f32_32x32x16_bf16 v[80:95], v[146:149], v[118:121], v[80:95]
	s_waitcnt lgkmcnt(0)
	v_mfma_f32_32x32x16_bf16 v[64:79], v[150:153], v[118:121], v[64:79]
	ds_read_b128 v[146:149], v193 offset:49152
	ds_read_b128 v[150:153], v193 offset:57344
	s_waitcnt lgkmcnt(1)
	v_mfma_f32_32x32x16_bf16 v[80:95], v[146:149], v[114:117], v[80:95]
	s_waitcnt lgkmcnt(0)
	v_mfma_f32_32x32x16_bf16 v[64:79], v[150:153], v[114:117], v[64:79]
	ds_read_b128 v[146:149], v207 offset:49152
	ds_read_b128 v[150:153], v207 offset:57344
	s_waitcnt lgkmcnt(1)
	v_mfma_f32_32x32x16_bf16 v[80:95], v[146:149], v[110:113], v[80:95]
	s_waitcnt lgkmcnt(0)
	v_mfma_f32_32x32x16_bf16 v[64:79], v[150:153], v[110:113], v[64:79]
	ds_read_b128 v[146:149], v206 offset:49152
	ds_read_b128 v[150:153], v206 offset:57344
	s_waitcnt lgkmcnt(1)
	v_mfma_f32_32x32x16_bf16 v[80:95], v[146:149], v[106:109], v[80:95]
	v_exp_f32_e32 v146, v176
	v_exp_f32_e32 v147, v177
	v_exp_f32_e32 v148, v174
	v_exp_f32_e32 v149, v175
	v_add_f32_e32 v162, v146, v162
	v_add_f32_e32 v162, v147, v162
	v_add_f32_e32 v162, v148, v162
	s_waitcnt lgkmcnt(0)
	v_mfma_f32_32x32x16_bf16 v[64:79], v[150:153], v[106:109], v[64:79]
	v_exp_f32_e32 v150, v170
	v_exp_f32_e32 v151, v171
	v_exp_f32_e32 v152, v166
	v_exp_f32_e32 v153, v167
	v_add_f32_e32 v162, v149, v162
	v_add_f32_e32 v162, v150, v162
	v_add_f32_e32 v162, v151, v162
	v_add_f32_e32 v162, v152, v162
	v_add_f32_e32 v162, v153, v162
	v_add_f32_e32 v162, v154, v162
	v_add_f32_e32 v162, v155, v162
	v_add_f32_e32 v162, v156, v162
	v_add_f32_e32 v162, v157, v162
	v_add_f32_e32 v162, v158, v162
	v_add_f32_e32 v162, v159, v162
	v_add_f32_e32 v162, v160, v162
	v_add_f32_e32 v211, v161, v162
	v_mov_b32_e32 v212, v211
	v_cvt_pk_bf16_f32 v162, v223, v224
	s_nop 0
	v_permlane32_swap_b32_e32 v211, v212
	v_permlane32_swap_b32_e32 v162, v164
	v_cvt_pk_bf16_f32 v166, v215, v217
	v_cvt_pk_bf16_f32 v167, v219, v221
	v_cvt_pk_bf16_f32 v170, v146, v147
	v_cvt_pk_bf16_f32 v171, v148, v149
	v_cvt_pk_bf16_f32 v172, v150, v151
	v_cvt_pk_bf16_f32 v173, v152, v153
	v_cvt_pk_bf16_f32 v174, v154, v155
	v_cvt_pk_bf16_f32 v175, v156, v157
	v_cvt_pk_bf16_f32 v176, v158, v159
	v_cvt_pk_bf16_f32 v177, v160, v161
	v_permlane32_swap_b32_e32 v166, v168
	v_permlane32_swap_b32_e32 v167, v169
	v_permlane32_swap_b32_e32 v170, v172
	v_permlane32_swap_b32_e32 v171, v173
	v_permlane32_swap_b32_e32 v174, v176
	v_permlane32_swap_b32_e32 v175, v177
	v_add_co_u32_e32 v146, vcc, s69, v182
	s_mov_b32 s8, 0xffff0000
	s_nop 0
	v_addc_co_u32_e32 v147, vcc, -1, v183, vcc
	v_add_co_u32_e32 v150, vcc, s8, v182
	s_mov_b32 s8, 0xff6e8000
	s_nop 0
	v_addc_co_u32_e32 v151, vcc, -1, v183, vcc
	v_add_co_u32_e32 v154, vcc, s8, v182
	s_mov_b32 s8, 0xff6f0000
	s_nop 0
	v_addc_co_u32_e32 v155, vcc, -1, v183, vcc
	v_add_co_u32_e32 v158, vcc, s8, v182
	global_load_dwordx4 v[146:149], v[146:147], off
	s_nop 0
	global_load_dwordx4 v[150:153], v[150:151], off
	v_addc_co_u32_e32 v159, vcc, -1, v183, vcc
	global_load_dwordx4 v[154:157], v[154:155], off
	s_nop 0
	global_load_dwordx4 v[158:161], v[158:159], off
	ds_read_b64_tr_b16 v[214:215], v179 offset:0
	ds_read_b64_tr_b16 v[216:217], v179 offset:0x800
	ds_read_b64_tr_b16 v[218:219], v179 offset:0x1000
	ds_read_b64_tr_b16 v[220:221], v179 offset:0x1800
	ds_read_b64_tr_b16 v[222:223], v179 offset:0x2000
	ds_read_b64_tr_b16 v[224:225], v179 offset:0x2800
	ds_read_b64_tr_b16 v[226:227], v179 offset:0x3000
	ds_read_b64_tr_b16 v[228:229], v179 offset:0x3800
	s_waitcnt vmcnt(4)
; __device__ __forceinline__ void partialSM(f32x16& p0, f32x16& p1, float& m_reg, float& mn, float& alpha) {
;   constexpr float C = SCALE * 1.4426950408889634f;
;   float pmax = p0[0]; for (int r = 1; r < 16; ++r) pmax = fmaxf(pmax, p0[r]); for (int r = 0; r < 16; ++r) pmax = fmaxf(pmax, p1[r]);
;   { auto rr = __builtin_amdgcn_permlane32_swap(__float_as_uint(pmax), __float_as_uint(pmax), false, false);
;     pmax = fmaxf(__uint_as_float(rr[0]), __uint_as_float(rr[1])); }
;   if (__builtin_expect(__all(pmax - m_reg <= THR / SCALE), 1)) { mn = m_reg; alpha = 1.f; }
;   else { mn = fmaxf(m_reg, pmax); alpha = __builtin_amdgcn_exp2f((m_reg - mn) * C); m_reg = mn; }
;   float mnC = -mn * C;
;   for (int r = 0; r < 16; ++r) p0[r] = fmaf(p0[r], C, mnC); for (int r = 0; r < 16; ++r) p1[r] = fmaf(p1[r], C, mnC);
;   for (int r = 0; r < 16; ++r) p0[r] = __builtin_amdgcn_exp2f(p0[r]);
; }
; __device__ __forceinline__ void finishSM(f32x16& p0, f32x16& p1, float alpha, float& l_reg, bf16x8& pa0, bf16x8& pa1, bf16x8& pa2, bf16x8& pa3) {
;   for (int r = 0; r < 16; ++r) p1[r] = __builtin_amdgcn_exp2f(p1[r]);
;   float ps = 0; for (int r = 0; r < 16; ++r) ps += p0[r]; for (int r = 0; r < 16; ++r) ps += p1[r];
;   { auto rr = __builtin_amdgcn_permlane32_swap(__float_as_uint(ps), __float_as_uint(ps), false, false);
;     ps = __uint_as_float(rr[0]) + __uint_as_float(rr[1]); }
;   l_reg = l_reg * alpha + ps;
;     ...
;   PK4(p0, 0, pa0); PK4(p0, 8, pa1); PK4(p1, 0, pa2); PK4(p1, 8, pa3);
;     ...
; }
; __device__ __forceinline__ void qkt(f32x16& p0, f32x16& p1, const bf16* Ks, const bf16x8* qr, int r32, int hi) {
;   p0 = f32x16{}; p1 = f32x16{};
;   for (int d0 = 0; d0 < 8; ++d0) { int cb = (d0 * 16 + hi * 8) * 2;
;     bf16x8 b0 = *reinterpret_cast<const bf16x8*>((const char*)Ks + KSWZ(r32, cb));
;     bf16x8 b1 = *reinterpret_cast<const bf16x8*>((const char*)Ks + KSWZ(32 + r32, cb));
;     p0 = __builtin_amdgcn_mfma_f32_32x32x16_bf16(b0, qr[d0], p0, 0, 0, 0);
;     p1 = __builtin_amdgcn_mfma_f32_32x32x16_bf16(b1, qr[d0], p1, 0, 0, 0); }
; }
; __device__ __forceinline__ int v_st(int k, int c) { const int kk = (k & ~0xC) | ((k & 4) << 1) | ((k & 8) >> 1); return ((kk >> 3) * 4 + (c >> 5)) * 512 + ((kk & 7) * 32 + (c & 31)) * 2; }
; __device__ __forceinline__ int v_rd_base(int lane) { return ((lane & 3) << 3) | (((lane >> 2) & 3) << 6) | (((lane >> 4) & 1) << 5) | (((lane >> 5) & 1) << 8); }
	ds_write_b128 v202, v[102:105] offset:32768
	ds_write_b128 v203, v[142:145] offset:32768
	s_waitcnt lgkmcnt(2)
	s_nop 0
	v_mfma_f32_32x32x16_bf16 v[0:15], v[162:165], v[214:217], v[0:15]
	ds_read_b64_tr_b16 v[214:215], v179 offset:0x200
	ds_read_b64_tr_b16 v[216:217], v179 offset:0xa00
	v_max_f32_e32 v232, v81, v81
	v_max_f32_e32 v233, v80, v80
	v_max_f32_e32 v232, v233, v232
	v_max3_f32 v232, v232, v82, v83
	v_max3_f32 v232, v232, v84, v85
	v_max3_f32 v232, v232, v86, v87
	v_mfma_f32_32x32x16_bf16 v[0:15], v[166:169], v[218:221], v[0:15]
	ds_read_b64_tr_b16 v[218:219], v179 offset:0x1200
	ds_read_b64_tr_b16 v[220:221], v179 offset:0x1a00
	v_max3_f32 v232, v232, v88, v89
	v_max3_f32 v232, v232, v90, v91
	v_max3_f32 v232, v232, v92, v93
	v_max3_f32 v232, v232, v94, v95
	v_max3_f32 v232, v232, v64, v65
	v_max3_f32 v232, v232, v66, v67
	v_mfma_f32_32x32x16_bf16 v[0:15], v[170:173], v[222:225], v[0:15]
	ds_read_b64_tr_b16 v[222:223], v179 offset:0x2200
	ds_read_b64_tr_b16 v[224:225], v179 offset:0x2a00
	v_max3_f32 v232, v232, v68, v69
	v_max3_f32 v232, v232, v70, v71
	v_max3_f32 v232, v232, v72, v73
	v_max3_f32 v232, v232, v74, v75
	v_max3_f32 v232, v232, v76, v77
	v_max3_f32 v232, v232, v78, v79
	v_mfma_f32_32x32x16_bf16 v[0:15], v[174:177], v[226:229], v[0:15]
	ds_read_b64_tr_b16 v[226:227], v179 offset:0x3200
	ds_read_b64_tr_b16 v[228:229], v179 offset:0x3a00
	v_mov_b32_e32 v233, v232
	s_nop 1
	v_permlane32_swap_b32_e32 v232, v233
	v_max_f32_e32 v233, v233, v233
	v_max_f32_e32 v232, v232, v232
	v_max_f32_e32 v232, v232, v233
	s_waitcnt lgkmcnt(0)
	v_mfma_f32_32x32x16_bf16 v[48:63], v[162:165], v[214:217], v[48:63]
	ds_read_b64_tr_b16 v[214:215], v179 offset:0x400
	ds_read_b64_tr_b16 v[216:217], v179 offset:0xc00
	v_sub_f32_e32 v233, v232, v210
	v_cmp_ge_f32_e32 vcc, s68, v233
	v_max_f32_e32 v233, v210, v210
	v_max_f32_e32 v232, v233, v232
	v_sub_f32_e32 v233, v210, v232
	v_mul_f32_e32 v233, 0x3e0293ee, v233
	v_mfma_f32_32x32x16_bf16 v[48:63], v[166:169], v[218:221], v[48:63]
	ds_read_b64_tr_b16 v[218:219], v179 offset:0x1400
	ds_read_b64_tr_b16 v[220:221], v179 offset:0x1c00
	s_cmp_eq_u64 vcc, exec
	s_cselect_b64 s[8:9], -1, 0
	v_exp_f32_e32 v233, v233
	v_mfma_f32_32x32x16_bf16 v[48:63], v[170:173], v[222:225], v[48:63]
	ds_read_b64_tr_b16 v[222:223], v179 offset:0x2400
	ds_read_b64_tr_b16 v[224:225], v179 offset:0x2c00
	v_cndmask_b32_e64 v210, v232, v210, s[8:9]
	v_mul_f32_e32 v213, 0xbe0293ee, v210
	v_fmamk_f32 v80, v80, 0x3e0293ee, v213
	v_fmamk_f32 v81, v81, 0x3e0293ee, v213
	v_fmamk_f32 v82, v82, 0x3e0293ee, v213
	v_fmamk_f32 v83, v83, 0x3e0293ee, v213
	v_mfma_f32_32x32x16_bf16 v[48:63], v[174:177], v[226:229], v[48:63]
	ds_read_b64_tr_b16 v[226:227], v179 offset:0x3400
	ds_read_b64_tr_b16 v[228:229], v179 offset:0x3c00
	v_fmamk_f32 v84, v84, 0x3e0293ee, v213
	v_fmamk_f32 v85, v85, 0x3e0293ee, v213
	v_fmamk_f32 v86, v86, 0x3e0293ee, v213
	v_fmamk_f32 v87, v87, 0x3e0293ee, v213
	v_fmamk_f32 v88, v88, 0x3e0293ee, v213
	v_fmamk_f32 v89, v89, 0x3e0293ee, v213
	s_waitcnt lgkmcnt(0)
	v_mfma_f32_32x32x16_bf16 v[32:47], v[162:165], v[214:217], v[32:47]
	ds_read_b64_tr_b16 v[214:215], v179 offset:0x600
	ds_read_b64_tr_b16 v[216:217], v179 offset:0xe00
	v_fmamk_f32 v90, v90, 0x3e0293ee, v213
	v_fmamk_f32 v91, v91, 0x3e0293ee, v213
	v_fmamk_f32 v92, v92, 0x3e0293ee, v213
	v_fmamk_f32 v93, v93, 0x3e0293ee, v213
	v_fmamk_f32 v94, v94, 0x3e0293ee, v213
	v_fmamk_f32 v95, v95, 0x3e0293ee, v213
	v_mfma_f32_32x32x16_bf16 v[32:47], v[166:169], v[218:221], v[32:47]
	ds_read_b64_tr_b16 v[218:219], v179 offset:0x1600
	ds_read_b64_tr_b16 v[220:221], v179 offset:0x1e00
	v_exp_f32_e32 v80, v80
	v_exp_f32_e32 v81, v81
	v_exp_f32_e32 v82, v82
	v_mfma_f32_32x32x16_bf16 v[32:47], v[170:173], v[222:225], v[32:47]
	ds_read_b64_tr_b16 v[222:223], v179 offset:0x2600
	ds_read_b64_tr_b16 v[224:225], v179 offset:0x2e00
	v_exp_f32_e32 v83, v83
	v_exp_f32_e32 v84, v84
	v_exp_f32_e32 v85, v85
	v_mfma_f32_32x32x16_bf16 v[32:47], v[174:177], v[226:229], v[32:47]
	ds_read_b64_tr_b16 v[226:227], v179 offset:0x3600
	ds_read_b64_tr_b16 v[228:229], v179 offset:0x3e00
	v_exp_f32_e32 v86, v86
	v_exp_f32_e32 v87, v87
	v_exp_f32_e32 v88, v88
	s_waitcnt lgkmcnt(0)
	v_mfma_f32_32x32x16_bf16 v[16:31], v[162:165], v[214:217], v[16:31]
	v_exp_f32_e32 v89, v89
	v_exp_f32_e32 v90, v90
	v_exp_f32_e32 v91, v91
	v_mfma_f32_32x32x16_bf16 v[16:31], v[166:169], v[218:221], v[16:31]
	v_exp_f32_e32 v92, v92
	v_exp_f32_e32 v93, v93
	v_mfma_f32_32x32x16_bf16 v[16:31], v[170:173], v[222:225], v[16:31]
	v_exp_f32_e32 v94, v94
	v_exp_f32_e32 v95, v95
	v_mfma_f32_32x32x16_bf16 v[16:31], v[174:177], v[226:229], v[16:31]
	s_barrier
	s_waitcnt vmcnt(4)
	v_cndmask_b32_e64 v214, v233, 1.0, s[8:9]
	v_cmp_gt_f32_e32 vcc, 1.0, v214
	s_waitcnt vmcnt(7)
	ds_write_b128 v204, v[98:101]
	s_waitcnt vmcnt(6)
	ds_write_b128 v205, v[138:141]
	s_cbranch_vccz .LBB0_606
	s_and_saveexec_b64 s[12:13], s[6:7]
	ds_write_b32 v189, v214 offset:128
	s_or_b64 exec, exec, s[12:13]
	s_waitcnt lgkmcnt(0)
	v_add_u32_e32 v163, v181, v180
	ds_read_b128 v[164:167], v163 offset:224
	ds_read_b128 v[168:171], v163 offset:192
	ds_read_b128 v[172:175], v163 offset:160
	ds_read_b128 v[216:219], v163 offset:128
	s_waitcnt lgkmcnt(3)
	v_pk_mul_f32 v[12:13], v[12:13], v[164:165]
	s_waitcnt lgkmcnt(2)
	v_pk_mul_f32 v[8:9], v[8:9], v[168:169]
	s_waitcnt lgkmcnt(1)
	v_pk_mul_f32 v[4:5], v[4:5], v[172:173]
	v_pk_mul_f32 v[14:15], v[14:15], v[166:167]
	v_pk_mul_f32 v[10:11], v[10:11], v[170:171]
	v_pk_mul_f32 v[6:7], v[6:7], v[174:175]
	s_waitcnt lgkmcnt(0)
	v_pk_mul_f32 v[2:3], v[2:3], v[218:219]
	v_pk_mul_f32 v[0:1], v[0:1], v[216:217]
	v_pk_mul_f32 v[60:61], v[60:61], v[164:165]
	v_pk_mul_f32 v[56:57], v[56:57], v[168:169]
	v_pk_mul_f32 v[52:53], v[52:53], v[172:173]
	v_pk_mul_f32 v[62:63], v[62:63], v[166:167]
	v_pk_mul_f32 v[58:59], v[58:59], v[170:171]
	v_pk_mul_f32 v[54:55], v[54:55], v[174:175]
	v_pk_mul_f32 v[50:51], v[50:51], v[218:219]
	v_pk_mul_f32 v[48:49], v[48:49], v[216:217]
	v_pk_mul_f32 v[44:45], v[44:45], v[164:165]
	v_pk_mul_f32 v[40:41], v[40:41], v[168:169]
	v_pk_mul_f32 v[36:37], v[36:37], v[172:173]
	v_pk_mul_f32 v[46:47], v[46:47], v[166:167]
	v_pk_mul_f32 v[42:43], v[42:43], v[170:171]
	v_pk_mul_f32 v[38:39], v[38:39], v[174:175]
	v_pk_mul_f32 v[34:35], v[34:35], v[218:219]
	v_pk_mul_f32 v[32:33], v[32:33], v[216:217]
	v_pk_mul_f32 v[28:29], v[28:29], v[164:165]
	v_pk_mul_f32 v[24:25], v[24:25], v[168:169]
	v_pk_mul_f32 v[20:21], v[20:21], v[172:173]
	v_pk_mul_f32 v[30:31], v[30:31], v[166:167]
	v_pk_mul_f32 v[26:27], v[26:27], v[170:171]
	v_pk_mul_f32 v[22:23], v[22:23], v[174:175]
	v_pk_mul_f32 v[18:19], v[18:19], v[218:219]
	v_pk_mul_f32 v[16:17], v[16:17], v[216:217]

; #define SBAR() __builtin_amdgcn_sched_barrier(0)
; template <int D0> __device__ __forceinline__ void pv_one(f32x16& od, int vb, bf16x8 pa0, bf16x8 pa1, bf16x8 pa2, bf16x8 pa3) {
;   const s16x4 l0 = tr_read<v_rd_off(D0, 0, 0)>(vb), h0 = tr_read<v_rd_off(D0, 0, 1)>(vb), l1 = tr_read<v_rd_off(D0, 1, 0)>(vb), h1 = tr_read<v_rd_off(D0, 1, 1)>(vb);
;   const s16x4 l2 = tr_read<v_rd_off(D0, 2, 0)>(vb), h2 = tr_read<v_rd_off(D0, 2, 1)>(vb), l3 = tr_read<v_rd_off(D0, 3, 0)>(vb), h3 = tr_read<v_rd_off(D0, 3, 1)>(vb);
;   asm volatile("s_waitcnt lgkmcnt(0)" ::: "memory"); SBAR();
.LBB0_608:
	ds_read_b64_tr_b16 v[216:217], v191 offset:0
	ds_read_b64_tr_b16 v[218:219], v191 offset:0x800
	ds_read_b64_tr_b16 v[220:221], v191 offset:0x1000
	ds_read_b64_tr_b16 v[222:223], v191 offset:0x1800
	ds_read_b64_tr_b16 v[224:225], v191 offset:0x2000
	ds_read_b64_tr_b16 v[226:227], v191 offset:0x2800
	ds_read_b64_tr_b16 v[242:243], v191 offset:0x3000
	ds_read_b64_tr_b16 v[244:245], v191 offset:0x3800
	s_cmp_lg_u64 s[12:13], 0
	s_cbranch_scc0 .Lk_w4
	s_waitcnt vmcnt(0)
	s_branch .Lk_wd
.Lk_w4:
	s_waitcnt vmcnt(4)
; __device__ __forceinline__ void partialSM(f32x16& p0, f32x16& p1, float& m_reg, float& mn, float& alpha) {
;   constexpr float C = SCALE * 1.4426950408889634f;
;   float pmax = p0[0]; for (int r = 1; r < 16; ++r) pmax = fmaxf(pmax, p0[r]); for (int r = 0; r < 16; ++r) pmax = fmaxf(pmax, p1[r]);
;   { auto rr = __builtin_amdgcn_permlane32_swap(__float_as_uint(pmax), __float_as_uint(pmax), false, false);
;     pmax = fmaxf(__uint_as_float(rr[0]), __uint_as_float(rr[1])); }
;   if (__builtin_expect(__all(pmax - m_reg <= THR / SCALE), 1)) { mn = m_reg; alpha = 1.f; }
;   else { mn = fmaxf(m_reg, pmax); alpha = __builtin_amdgcn_exp2f((m_reg - mn) * C); m_reg = mn; }
;   float mnC = -mn * C;
;   for (int r = 0; r < 16; ++r) p0[r] = fmaf(p0[r], C, mnC); for (int r = 0; r < 16; ++r) p1[r] = fmaf(p1[r], C, mnC);
;   for (int r = 0; r < 16; ++r) p0[r] = __builtin_amdgcn_exp2f(p0[r]);
; }
; __device__ __forceinline__ void finishSM(f32x16& p0, f32x16& p1, float alpha, float& l_reg, bf16x8& pa0, bf16x8& pa1, bf16x8& pa2, bf16x8& pa3) {
;   for (int r = 0; r < 16; ++r) p1[r] = __builtin_amdgcn_exp2f(p1[r]);
;   float ps = 0; for (int r = 0; r < 16; ++r) ps += p0[r]; for (int r = 0; r < 16; ++r) ps += p1[r];
;   { auto rr = __builtin_amdgcn_permlane32_swap(__float_as_uint(ps), __float_as_uint(ps), false, false);
;     ps = __uint_as_float(rr[0]) + __uint_as_float(rr[1]); }
;   l_reg = l_reg * alpha + ps;
;     ...
;   PK4(p0, 0, pa0); PK4(p0, 8, pa1); PK4(p1, 0, pa2); PK4(p1, 8, pa3);
;     ...
; }
; __device__ __forceinline__ void qkt(f32x16& p0, f32x16& p1, const bf16* Ks, const bf16x8* qr, int r32, int hi) {
;   p0 = f32x16{}; p1 = f32x16{};
;   for (int d0 = 0; d0 < 8; ++d0) { int cb = (d0 * 16 + hi * 8) * 2;
;     bf16x8 b0 = *reinterpret_cast<const bf16x8*>((const char*)Ks + KSWZ(r32, cb));
;     bf16x8 b1 = *reinterpret_cast<const bf16x8*>((const char*)Ks + KSWZ(32 + r32, cb));
;     p0 = __builtin_amdgcn_mfma_f32_32x32x16_bf16(b0, qr[d0], p0, 0, 0, 0);
;     p1 = __builtin_amdgcn_mfma_f32_32x32x16_bf16(b1, qr[d0], p1, 0, 0, 0); }
; }
; __device__ __forceinline__ int v_st(int k, int c) { const int kk = (k & ~0xC) | ((k & 4) << 1) | ((k & 8) >> 1); return ((kk >> 3) * 4 + (c >> 5)) * 512 + ((kk & 7) * 32 + (c & 31)) * 2; }
; __device__ __forceinline__ int v_rd_base(int lane) { return ((lane & 3) << 3) | (((lane >> 2) & 3) << 6) | (((lane >> 4) & 1) << 5) | (((lane >> 5) & 1) << 8); }
.Lk_wd:
	ds_write_b128 v202, v[154:157] offset:49152
	ds_write_b128 v203, v[158:161] offset:49152
	s_waitcnt lgkmcnt(2)
	s_nop 0
	v_mfma_f32_32x32x16_bf16 v[0:15], v[162:165], v[216:219], v[0:15]
	ds_read_b64_tr_b16 v[216:217], v191 offset:0x200
	ds_read_b64_tr_b16 v[218:219], v191 offset:0xa00
	v_max_f32_e32 v232, v81, v81
	v_max_f32_e32 v233, v80, v80
	v_max_f32_e32 v232, v233, v232
	v_max3_f32 v232, v232, v82, v83
	v_max3_f32 v232, v232, v84, v85
	v_max3_f32 v232, v232, v86, v87
	v_mfma_f32_32x32x16_bf16 v[0:15], v[166:169], v[220:223], v[0:15]
	ds_read_b64_tr_b16 v[220:221], v191 offset:0x1200
	ds_read_b64_tr_b16 v[222:223], v191 offset:0x1a00
	v_max3_f32 v232, v232, v88, v89
	v_max3_f32 v232, v232, v90, v91
	v_max3_f32 v232, v232, v92, v93
	v_max3_f32 v232, v232, v94, v95
	v_max3_f32 v232, v232, v64, v65
	v_max3_f32 v232, v232, v66, v67
	v_mfma_f32_32x32x16_bf16 v[0:15], v[170:173], v[224:227], v[0:15]
	ds_read_b64_tr_b16 v[224:225], v191 offset:0x2200
	ds_read_b64_tr_b16 v[226:227], v191 offset:0x2a00
	v_max3_f32 v232, v232, v68, v69
	v_max3_f32 v232, v232, v70, v71
	v_max3_f32 v232, v232, v72, v73
	v_max3_f32 v232, v232, v74, v75
	v_max3_f32 v232, v232, v76, v77
	v_max3_f32 v232, v232, v78, v79
	v_mfma_f32_32x32x16_bf16 v[0:15], v[174:177], v[242:245], v[0:15]
	ds_read_b64_tr_b16 v[242:243], v191 offset:0x3200
	ds_read_b64_tr_b16 v[244:245], v191 offset:0x3a00
	v_mov_b32_e32 v233, v232
	s_nop 1
	v_permlane32_swap_b32_e32 v232, v233
	v_max_f32_e32 v233, v233, v233
	v_max_f32_e32 v232, v232, v232
	v_max_f32_e32 v232, v232, v233
	s_waitcnt lgkmcnt(0)
	v_mfma_f32_32x32x16_bf16 v[48:63], v[162:165], v[216:219], v[48:63]
	ds_read_b64_tr_b16 v[216:217], v191 offset:0x400
	ds_read_b64_tr_b16 v[218:219], v191 offset:0xc00
	v_sub_f32_e32 v233, v232, v210
	v_cmp_ge_f32_e32 vcc, s68, v233
	v_max_f32_e32 v233, v210, v210
	v_max_f32_e32 v232, v233, v232
	v_sub_f32_e32 v233, v210, v232
	v_mul_f32_e32 v233, 0x3e0293ee, v233
	v_mfma_f32_32x32x16_bf16 v[48:63], v[166:169], v[220:223], v[48:63]
	ds_read_b64_tr_b16 v[220:221], v191 offset:0x1400
	ds_read_b64_tr_b16 v[222:223], v191 offset:0x1c00
	s_cmp_eq_u64 vcc, exec
	s_cselect_b64 s[8:9], -1, 0
	v_exp_f32_e32 v233, v233
	v_mfma_f32_32x32x16_bf16 v[48:63], v[170:173], v[224:227], v[48:63]
	ds_read_b64_tr_b16 v[224:225], v191 offset:0x2400
	ds_read_b64_tr_b16 v[226:227], v191 offset:0x2c00
	v_cndmask_b32_e64 v210, v232, v210, s[8:9]
	v_mul_f32_e32 v250, 0xbe0293ee, v210
	v_fmamk_f32 v80, v80, 0x3e0293ee, v250
	v_fmamk_f32 v81, v81, 0x3e0293ee, v250
	v_fmamk_f32 v82, v82, 0x3e0293ee, v250
	v_fmamk_f32 v83, v83, 0x3e0293ee, v250
	v_mfma_f32_32x32x16_bf16 v[48:63], v[174:177], v[242:245], v[48:63]
	ds_read_b64_tr_b16 v[242:243], v191 offset:0x3400
	ds_read_b64_tr_b16 v[244:245], v191 offset:0x3c00
	v_fmamk_f32 v84, v84, 0x3e0293ee, v250
	v_fmamk_f32 v85, v85, 0x3e0293ee, v250
	v_fmamk_f32 v86, v86, 0x3e0293ee, v250
	v_fmamk_f32 v87, v87, 0x3e0293ee, v250
	v_fmamk_f32 v88, v88, 0x3e0293ee, v250
	v_fmamk_f32 v89, v89, 0x3e0293ee, v250
	s_waitcnt lgkmcnt(0)
	v_mfma_f32_32x32x16_bf16 v[32:47], v[162:165], v[216:219], v[32:47]
	ds_read_b64_tr_b16 v[216:217], v191 offset:0x600
	ds_read_b64_tr_b16 v[218:219], v191 offset:0xe00
	v_fmamk_f32 v90, v90, 0x3e0293ee, v250
	v_fmamk_f32 v91, v91, 0x3e0293ee, v250
	v_fmamk_f32 v92, v92, 0x3e0293ee, v250
	v_fmamk_f32 v93, v93, 0x3e0293ee, v250
	v_fmamk_f32 v94, v94, 0x3e0293ee, v250
	v_fmamk_f32 v95, v95, 0x3e0293ee, v250
	v_mfma_f32_32x32x16_bf16 v[32:47], v[166:169], v[220:223], v[32:47]
	ds_read_b64_tr_b16 v[220:221], v191 offset:0x1600
	ds_read_b64_tr_b16 v[222:223], v191 offset:0x1e00
	v_exp_f32_e32 v80, v80
	v_exp_f32_e32 v81, v81
	v_exp_f32_e32 v82, v82
	v_mfma_f32_32x32x16_bf16 v[32:47], v[170:173], v[224:227], v[32:47]
	ds_read_b64_tr_b16 v[224:225], v191 offset:0x2600
	ds_read_b64_tr_b16 v[226:227], v191 offset:0x2e00
	v_exp_f32_e32 v83, v83
	v_exp_f32_e32 v84, v84
	v_exp_f32_e32 v85, v85
	v_mfma_f32_32x32x16_bf16 v[32:47], v[174:177], v[242:245], v[32:47]
	ds_read_b64_tr_b16 v[242:243], v191 offset:0x3600
	ds_read_b64_tr_b16 v[244:245], v191 offset:0x3e00
	v_exp_f32_e32 v86, v86
	v_exp_f32_e32 v87, v87
	v_exp_f32_e32 v88, v88
	s_waitcnt lgkmcnt(0)
	v_mfma_f32_32x32x16_bf16 v[16:31], v[162:165], v[216:219], v[16:31]
	v_exp_f32_e32 v89, v89
	v_exp_f32_e32 v90, v90
	v_exp_f32_e32 v91, v91
	v_mfma_f32_32x32x16_bf16 v[16:31], v[166:169], v[220:223], v[16:31]
	v_exp_f32_e32 v92, v92
	v_exp_f32_e32 v93, v93
	v_mfma_f32_32x32x16_bf16 v[16:31], v[170:173], v[224:227], v[16:31]
	v_exp_f32_e32 v94, v94
	v_exp_f32_e32 v95, v95
	v_mfma_f32_32x32x16_bf16 v[16:31], v[174:177], v[242:245], v[16:31]
	s_barrier
	s_waitcnt vmcnt(4)
	v_cndmask_b32_e64 v213, v233, 1.0, s[8:9]
	v_cmp_gt_f32_e32 vcc, 1.0, v213
	ds_write_b128 v204, v[146:149] offset:16384
	ds_write_b128 v205, v[150:153] offset:16384
	s_cbranch_vccz .LBB0_612
	s_and_saveexec_b64 s[18:19], s[6:7]
	ds_write_b32 v189, v213 offset:128
	s_or_b64 exec, exec, s[18:19]
	s_waitcnt lgkmcnt(0)
	v_add_u32_e32 v158, v181, v180
	ds_read_b128 v[146:149], v158 offset:224
	ds_read_b128 v[150:153], v158 offset:192
	ds_read_b128 v[154:157], v158 offset:160
	ds_read_b128 v[158:161], v158 offset:128
	s_waitcnt lgkmcnt(3)
	v_pk_mul_f32 v[12:13], v[12:13], v[146:147]
	s_waitcnt lgkmcnt(2)
	v_pk_mul_f32 v[8:9], v[8:9], v[150:151]
	s_waitcnt lgkmcnt(1)
	v_pk_mul_f32 v[4:5], v[4:5], v[154:155]
	v_pk_mul_f32 v[14:15], v[14:15], v[148:149]
	v_pk_mul_f32 v[10:11], v[10:11], v[152:153]
	v_pk_mul_f32 v[6:7], v[6:7], v[156:157]
	s_waitcnt lgkmcnt(0)
	v_pk_mul_f32 v[2:3], v[2:3], v[160:161]
	v_pk_mul_f32 v[0:1], v[0:1], v[158:159]
	v_pk_mul_f32 v[60:61], v[60:61], v[146:147]
	v_pk_mul_f32 v[56:57], v[56:57], v[150:151]
	v_pk_mul_f32 v[52:53], v[52:53], v[154:155]
	v_pk_mul_f32 v[62:63], v[62:63], v[148:149]
	v_pk_mul_f32 v[58:59], v[58:59], v[152:153]
	v_pk_mul_f32 v[54:55], v[54:55], v[156:157]
	v_pk_mul_f32 v[50:51], v[50:51], v[160:161]
	v_pk_mul_f32 v[48:49], v[48:49], v[158:159]
	v_pk_mul_f32 v[44:45], v[44:45], v[146:147]
	v_pk_mul_f32 v[40:41], v[40:41], v[150:151]
	v_pk_mul_f32 v[36:37], v[36:37], v[154:155]
	v_pk_mul_f32 v[46:47], v[46:47], v[148:149]
	v_pk_mul_f32 v[42:43], v[42:43], v[152:153]
	v_pk_mul_f32 v[38:39], v[38:39], v[156:157]
	v_pk_mul_f32 v[34:35], v[34:35], v[160:161]
	v_pk_mul_f32 v[32:33], v[32:33], v[158:159]
	v_pk_mul_f32 v[28:29], v[28:29], v[146:147]
	v_pk_mul_f32 v[24:25], v[24:25], v[150:151]
	v_pk_mul_f32 v[20:21], v[20:21], v[154:155]
	v_pk_mul_f32 v[30:31], v[30:31], v[148:149]
	v_pk_mul_f32 v[26:27], v[26:27], v[152:153]
	v_pk_mul_f32 v[22:23], v[22:23], v[156:157]
	v_pk_mul_f32 v[18:19], v[18:19], v[160:161]
	v_pk_mul_f32 v[16:17], v[16:17], v[158:159]
